# gla_scan: V^T fragments fetched once per workgroup by LDS-DMA into a 4-slot ring and shared via ds_read (was 8x redundant through L1)
# baseline (speedup 1.0000x reference)
; #define LAS __attribute__((address_space(3)))
; __device__ __forceinline__ void gla_scan(LAS unsigned char* lds, int bx, int G, const bf16_t* KS, const bf16_t* QD, const bf16_t* VT, const float* DEC, bf16_t* Of, bf16_t* Ob) {
;     int tid = threadIdx.x; asm volatile("" : "+v"(tid));
;     const int lane = tid & 63, wave = __builtin_amdgcn_readfirstlane(tid >> 6), fr = lane & 15, fq = lane >> 4;
;     LAS bf16_t* ST = (LAS bf16_t*)lds;
;     for (int unit = bx; unit < 256; unit += G) {
;         const int vs = unit & 7, dir = (unit >> 3) & 1, bh = unit >> 4, b = bh >> 2, h = bh & 3;
;         bf16_t* O = dir ? Ob : Of;
;         f32x4 S0 = (f32x4){0.f, 0.f, 0.f, 0.f}, S1 = S0;
;         const bf16x8 z8 = (bf16x8){0, 0, 0, 0, 0, 0, 0, 0};
;     ...
;         GLB_DECL(a_) GLB_DECL(b_) GLB_DECL(c_) GLB_DECL(d_)
;     ...
;         __syncthreads();
;         GLB_LOAD(0, a_); GLB_LOAD(1, b_); GLB_LOAD(2, c_);
;         GLB_LOAD(3, d_); GLB_STEP(0, a_, false);
.LBB0_1278:
	s_or_b64 exec, exec, s[4:5]
	s_and_b32 s33, s88, 7
	s_ashr_i32 s5, s88, 3
	s_lshl_b32 s4, s33, 5
	s_and_b32 s5, s5, -8
	s_add_i32 s4, s4, s5
	s_bfe_u32 s5, s88, 0x30003
	s_or_b32 s10, s4, s5
	s_waitcnt lgkmcnt(0)
	v_mov_b32_e32 v0, v189
	s_barrier
	s_cmpk_gt_i32 s10, 0xff
	v_readfirstlane_b32 s4, v0
	s_cbranch_scc1 .LBB0_1283
	v_and_b32_e32 v2, 63, v0
	v_and_b32_e32 v1, 15, v0
	s_ashr_i32 s6, s4, 6
	v_lshlrev_b32_e32 v176, 3, v2
	v_lshl_or_b32 v2, s6, 10, v176
	v_lshl_or_b32 v193, s6, 4, v1
	s_and_b32 s7, s6, 1
	s_lshl_b32 s6, s6, 5
	s_add_i32 s6, s6, 0
	v_lshl_add_u32 v5, v1, 1, s6
	v_lshl_or_b32 v1, s7, 4, v1
	v_ashrrev_i32_e32 v3, 31, v2
	s_ashr_i32 s4, s4, 7
	v_mul_u32_u24_e32 v1, 0x88, v1
	v_bfe_u32 v4, v0, 4, 2
	v_lshl_add_u64 v[178:179], v[2:3], 1, s[64:65]
	v_lshl_or_b32 v2, s4, 11, v176
	s_ashr_i32 s5, s4, 31
	v_lshlrev_b32_e32 v1, 1, v1
	v_and_b32_e32 v0, 48, v0
	v_ashrrev_i32_e32 v3, 31, v2
	v_mov_b32_e32 v183, 0
	v_add3_u32 v210, 0, v1, v0
	v_mul_u32_u24_e32 v0, 0x440, v4
	s_lshl_b64 s[4:5], s[4:5], 10
	s_lshl_b32 s6, s7, 9
	v_lshl_add_u64 v[180:181], v[2:3], 1, s[86:87]
	v_mov_b32_e32 v177, v183
	s_or_b32 s4, s4, s6
	v_lshlrev_b32_e32 v211, 1, v176
	v_add_u32_e32 v212, v5, v0
	v_readlane_b32 s34, v254, 58
	v_readlane_b32 s35, v254, 59
	v_readfirstlane_b32 s98, v189
	s_lshr_b32 s98, s98, 6
	s_and_b32 s98, s98, 3
	s_lshl_b32 s98, s98, 10
	v_mov_b32_e32 v248, s98
	v_mov_b32_e32 v249, 0
	s_add_i32 s98, s98, 0x8000
	s_add_i32 s99, s98, 0x1000
	s_add_i32 s100, s98, 0x2000
	s_add_i32 s101, s98, 0x3000
	v_and_b32_e32 v250, 63, v189
	v_lshlrev_b32_e32 v250, 4, v250
	v_add_u32_e32 v250, 0x8000, v250
.LBB0_1280:
	s_bfe_i32 s6, s10, 0x10003
	s_ashr_i32 s18, s10, 4
	s_bfe_u32 s17, s10, 0x10003
	s_and_b32 s13, s6, 3
	s_lshl_b32 s6, s18, 1
	s_or_b32 s19, s6, s17
	s_mul_i32 s11, s19, 36
	s_mul_i32 s12, s18, 36
	s_or_b32 s6, s11, s13
	s_or_b32 s14, s13, s12
	s_ashr_i32 s7, s6, 31
	s_ashr_i32 s15, s14, 31
	s_and_b32 s16, s10, 7
	s_lshl_b64 s[8:9], s[6:7], 14
	s_lshl_b64 s[14:15], s[14:15], 15
	s_add_u32 s14, s54, s14
	s_addc_u32 s15, s55, s15
	v_lshl_or_b32 v182, s16, 12, v211
	s_waitcnt vmcnt(29)
	v_lshl_add_u32 v4, s6, 7, v193
	s_barrier
	v_add_u32_e32 v246, v182, v248
	s_mov_b32 m0, s98
	s_nop 0
	global_load_lds_dwordx4 v246, s[14:15]
	v_ashrrev_i32_e32 v5, 31, v4
	v_lshl_add_u64 v[4:5], v[4:5], 2, s[2:3]
	global_load_dword v30, v[4:5], off
	s_waitcnt vmcnt(18)
	v_lshl_add_u64 v[12:13], v[178:179], 0, s[8:9]
	global_load_dword v251, v249, s[54:55]
	global_load_dwordx4 v[8:11], v[12:13], off
	s_nop 0
	global_load_dwordx4 v[12:15], v[12:13], off offset:1024
	s_nop 0
	global_load_dword v251, v249, s[54:55]
	global_load_dword v251, v249, s[54:55]
	s_add_i32 s6, s17, 1
	s_or_b32 s8, s11, s6
	s_or_b32 s6, s6, s12
	s_ashr_i32 s13, s10, 1
	s_ashr_i32 s9, s8, 31
	s_ashr_i32 s7, s6, 31
	s_andn2_b32 s13, s13, 31
	s_lshl_b64 s[14:15], s[8:9], 14
	s_lshl_b64 s[6:7], s[6:7], 15
	v_lshl_add_u32 v26, s8, 7, v193
	s_add_u32 s20, s54, s6
	v_lshl_add_u64 v[24:25], v[178:179], 0, s[14:15]
	v_ashrrev_i32_e32 v27, 31, v26
	s_addc_u32 s21, s55, s7
	global_load_dwordx4 v[72:75], v[24:25], off
	v_add_u32_e32 v246, v182, v248
	s_mov_b32 m0, s99
	s_nop 0
	global_load_lds_dwordx4 v246, s[20:21]
	global_load_dword v251, v249, s[54:55]
	global_load_dword v251, v249, s[54:55]
	global_load_dword v251, v249, s[54:55]
	v_lshl_add_u64 v[26:27], v[26:27], 2, s[2:3]
	global_load_dwordx4 v[92:95], v[24:25], off offset:1024
	global_load_dword v108, v[26:27], off
	s_sub_i32 s6, 2, s17
	s_or_b32 s22, s11, s6
	s_or_b32 s6, s6, s12
	s_ashr_i32 s23, s22, 31
	s_ashr_i32 s7, s6, 31
	s_lshl_b64 s[24:25], s[22:23], 14
	s_lshl_b64 s[6:7], s[6:7], 15
	s_add_u32 s26, s54, s6
	s_addc_u32 s27, s55, s7
	s_cmp_eq_u32 s17, 0
	s_cselect_b64 s[6:7], -1, 0
	s_and_b64 s[8:9], s[6:7], exec
	v_lshl_add_u64 v[24:25], v[178:179], 0, s[24:25]
	s_cselect_b32 s21, 3, 0
	global_load_dwordx4 v[60:63], v[24:25], off
	global_load_dwordx4 v[56:59], v[24:25], off offset:1024
	v_add_u32_e32 v246, v182, v248
	s_mov_b32 m0, s100
	s_nop 0
	global_load_lds_dwordx4 v246, s[26:27]
	global_load_dword v251, v249, s[54:55]
	global_load_dword v251, v249, s[54:55]
	global_load_dword v251, v249, s[54:55]
	v_lshl_add_u32 v24, s22, 7, v193
	s_cselect_b32 s9, s83, s81
	s_cselect_b32 s8, s82, s80
	s_cselect_b32 s26, 4, 35
	s_cselect_b32 s20, 5, 34
	s_cselect_b32 s17, 6, 33
	s_or_b32 s14, s11, s21
	v_ashrrev_i32_e32 v25, 31, v24
	s_ashr_i32 s15, s14, 31
	v_lshl_add_u64 v[24:25], v[24:25], 2, s[2:3]
	s_lshl_b64 s[22:23], s[14:15], 14
	v_lshl_add_u64 v[28:29], v[178:179], 0, s[22:23]
	global_load_dword v112, v[24:25], off
	global_load_dwordx4 v[120:123], v[28:29], off
	s_or_b32 s22, s21, s12
	s_ashr_i32 s23, s22, 31
	s_lshl_b64 s[22:23], s[22:23], 15
	s_add_u32 s22, s54, s22
	s_addc_u32 s23, s55, s23
	v_add_u32_e32 v246, v182, v248
	s_mov_b32 m0, s101
	s_nop 0
	global_load_lds_dwordx4 v246, s[22:23]
	global_load_dword v251, v249, s[54:55]
	global_load_dword v251, v249, s[54:55]
	global_load_dword v251, v249, s[54:55]
	s_add_i32 s22, s11, s26
	s_ashr_i32 s23, s22, 31
	s_lshl_b64 s[24:25], s[22:23], 14
	v_lshl_add_u64 v[184:185], s[54:55], 0, v[182:183]
	s_waitcnt vmcnt(24)
	v_mul_f32_e32 v24, 0, v30
	v_mov_b32_e32 v25, v24
	v_mov_b32_e32 v26, v24
	v_mov_b32_e32 v27, v24
	s_waitcnt vmcnt(22)
	s_nop 0
	s_waitcnt vmcnt(0)
	s_barrier
; __device__ __forceinline__ void gla_scan(LAS unsigned char* lds, int bx, int G, const bf16_t* KS, const bf16_t* QD, const bf16_t* VT, const float* DEC, bf16_t* Of, bf16_t* Ob) {
;     ...
;         __syncthreads();
;         GLB_LOAD(0, a_); GLB_LOAD(1, b_); GLB_LOAD(2, c_);
;         GLB_LOAD(3, d_); GLB_STEP(0, a_, false);
;         GLB_LOAD(4, a_); GLB_STEP(1, b_, false);
;         GLB_LOAD(5, b_); GLB_STEP(2, c_, false);
;         GLB_LOAD(6, c_); GLB_STEP(3, d_, false);
	ds_read_b128 v[0:3], v250 offset:0
	ds_read_b128 v[4:7], v250 offset:1024
	ds_read_b128 v[16:19], v250 offset:2048
	ds_read_b128 v[20:23], v250 offset:3072
	ds_read_b128 v[76:79], v250 offset:4096
	ds_read_b128 v[80:83], v250 offset:5120
	ds_read_b128 v[84:87], v250 offset:6144
	ds_read_b128 v[88:91], v250 offset:7168
	s_waitcnt lgkmcnt(0)
	v_mfma_f32_16x16x32_bf16 v[0:3], v[0:3], v[8:11], v[24:27]
	s_waitcnt vmcnt(21)
	v_mfma_f32_16x16x32_bf16 v[104:107], v[4:7], v[12:15], v[0:3]
	v_lshl_add_u32 v4, s14, 7, v193
	v_ashrrev_i32_e32 v5, 31, v4
	v_lshl_add_u64 v[4:5], v[4:5], 2, s[2:3]
	global_load_dwordx4 v[136:139], v[28:29], off offset:1024
	global_load_dword v144, v[4:5], off
	s_waitcnt vmcnt(22)
	v_mfma_f32_16x16x32_bf16 v[0:3], v[16:19], v[8:11], v[24:27]
	s_lshl_b32 s14, s19, 5
	s_waitcnt vmcnt(21)
	v_mfma_f32_16x16x32_bf16 v[8:11], v[20:23], v[12:15], v[0:3]
	s_waitcnt vmcnt(14)
	v_pk_mul_f32 v[14:15], v[108:109], v[106:107] op_sel_hi:[0,1]
	v_pk_mul_f32 v[12:13], v[108:109], v[104:105] op_sel_hi:[0,1]
	s_nop 1
	v_cvt_pk_bf16_f32 v0, v104, s0
	ds_write_b16 v212, v0
	s_nop 0
	v_cvt_pk_bf16_f32 v0, v8, s0
	ds_write_b16 v212, v0 offset:4352
	v_cvt_pk_bf16_f32 v0, v105, s0
	ds_write_b16 v212, v0 offset:272
	v_cvt_pk_bf16_f32 v0, v9, s0
	ds_write_b16 v212, v0 offset:4624
	v_cvt_pk_bf16_f32 v0, v106, s0
	ds_write_b16 v212, v0 offset:544
	v_cvt_pk_bf16_f32 v0, v10, s0
	ds_write_b16 v212, v0 offset:4896
	v_cvt_pk_bf16_f32 v0, v107, s0
	ds_write_b16 v212, v0 offset:816
	v_cvt_pk_bf16_f32 v0, v11, s0
	ds_write_b16 v212, v0 offset:5168
	v_lshl_add_u64 v[0:1], v[178:179], 0, s[24:25]
	s_add_i32 s24, s26, s12
	s_ashr_i32 s25, s24, 31
	s_lshl_b64 s[24:25], s[24:25], 15
	s_add_u32 s24, s54, s24
	v_mfma_f32_16x16x32_bf16 v[12:15], v[76:79], v[72:75], v[12:15]
	v_mul_f32_e64 v10, v108, v10
	v_mul_f32_e64 v11, v108, v11
	v_pk_mul_f32 v[8:9], v[108:109], v[8:9] op_sel_hi:[0,1]
	s_waitcnt lgkmcnt(0)
	s_waitcnt vmcnt(11)
	s_barrier
	ds_read_b128 v[100:103], v250 offset:8192
	ds_read_b128 v[96:99], v250 offset:9216
	ds_read_b128 v[68:71], v250 offset:10240
	ds_read_b128 v[64:67], v250 offset:11264
	s_waitcnt lgkmcnt(0)
	s_addc_u32 s25, s55, s25
	s_add_i32 s15, s26, -4
	v_mfma_f32_16x16x32_bf16 v[8:11], v[84:87], v[72:75], v[8:11]
	global_load_dwordx4 v[44:47], v[0:1], off
	global_load_dwordx4 v[28:31], v[0:1], off offset:1024
	v_lshl_add_u32 v0, s22, 7, v193
	s_add_i32 s22, s15, s14
	s_ashr_i32 s23, s22, 31
	s_lshl_b64 s[22:23], s[22:23], 14
	s_lshl_b32 s18, s18, 3
	v_mfma_f32_16x16x32_bf16 v[104:107], v[80:83], v[92:95], v[12:15]
	v_lshl_add_u64 v[2:3], v[180:181], 0, s[22:23]
	s_add_i32 s22, s15, s13
	s_and_b32 s18, s18, 24
	v_mfma_f32_16x16x32_bf16 v[108:111], v[88:91], v[92:95], v[8:11]
	s_ashr_i32 s23, s22, 31
	s_or_b32 s18, s18, s16
	v_ashrrev_i32_e32 v1, 31, v0
	s_lshl_b64 s[22:23], s[22:23], 17
	s_lshl_b32 s19, s18, 12
	v_lshl_add_u64 v[0:1], v[0:1], 2, s[2:3]
	s_or_b32 s16, s22, s19
	v_cvt_pk_bf16_f32 v8, v104, s0
	v_add_u32_e32 v246, v182, v248
	s_mov_b32 m0, s98
	s_nop 0
	global_load_lds_dwordx4 v246, s[24:25]
	global_load_dword v251, v249, s[54:55]
	global_load_dword v251, v249, s[54:55]
	global_load_dword v251, v249, s[54:55]
	global_load_dword v192, v[0:1], off
	global_load_dwordx4 v[32:35], v[2:3], off
	global_load_dwordx4 v[24:27], v[2:3], off offset:1024
	global_load_dwordx4 v[4:7], v[2:3], off offset:2048
	s_nop 0
	global_load_dwordx4 v[0:3], v[2:3], off offset:3072
	s_add_u32 s16, s8, s16
	ds_write_b16 v212, v8 offset:8704
	v_cvt_pk_bf16_f32 v8, v108, s0
	s_addc_u32 s21, s9, s23
	ds_write_b16 v212, v8 offset:13056
	v_cvt_pk_bf16_f32 v8, v105, s0
	s_add_u32 s22, s16, s4
	ds_write_b16 v212, v8 offset:8976
	v_cvt_pk_bf16_f32 v8, v109, s0
	s_addc_u32 s23, s21, s5
	ds_write_b16 v212, v8 offset:13328
	v_cvt_pk_bf16_f32 v8, v106, s0
	v_lshl_add_u64 v[12:13], s[22:23], 0, v[176:177]
	ds_write_b16 v212, v8 offset:9248
	v_cvt_pk_bf16_f32 v8, v110, s0
	s_add_i32 s22, s11, s20
	ds_write_b16 v212, v8 offset:13600
	v_cvt_pk_bf16_f32 v8, v107, s0
	s_ashr_i32 s23, s22, 31
	s_waitcnt vmcnt(18)
	v_pk_mul_f32 v[106:107], v[112:113], v[106:107] op_sel_hi:[0,1]
	v_pk_mul_f32 v[104:105], v[112:113], v[104:105] op_sel_hi:[0,1]
	ds_write_b16 v212, v8 offset:9520
	v_cvt_pk_bf16_f32 v8, v111, s0
	s_lshl_b64 s[24:25], s[22:23], 14
	v_mfma_f32_16x16x32_bf16 v[100:103], v[100:103], v[60:63], v[104:107]
	ds_write_b16 v212, v8 offset:13872
	v_lshl_add_u64 v[8:9], v[178:179], 0, s[24:25]
	s_add_i32 s24, s20, s12
	s_ashr_i32 s25, s24, 31
	s_lshl_b64 s[24:25], s[24:25], 15
	s_add_u32 s24, s54, s24
	v_mfma_f32_16x16x32_bf16 v[146:149], v[96:99], v[56:59], v[100:103]
	v_mul_f32_e64 v98, v112, v110
	v_mul_f32_e64 v99, v112, v111
	v_pk_mul_f32 v[96:97], v[112:113], v[108:109] op_sel_hi:[0,1]
	s_addc_u32 s25, s55, s25
	s_add_i32 s16, s20, -4
	v_mfma_f32_16x16x32_bf16 v[60:63], v[68:71], v[60:63], v[96:99]
	s_add_i32 s20, s16, s14
	s_ashr_i32 s21, s20, 31
	s_lshl_b64 s[20:21], s[20:21], 14
	global_load_dwordx2 v[196:197], v[12:13], off
	s_waitcnt lgkmcnt(0)
	s_barrier
; __device__ __forceinline__ void gla_scan(LAS unsigned char* lds, int bx, int G, const bf16_t* KS, const bf16_t* QD, const bf16_t* VT, const float* DEC, bf16_t* Of, bf16_t* Ob) {
;     ...
;         GLB_LOAD(0, a_); GLB_LOAD(1, b_); GLB_LOAD(2, c_);
;         GLB_LOAD(3, d_); GLB_STEP(0, a_, false);
;         GLB_LOAD(4, a_); GLB_STEP(1, b_, false);
;         GLB_LOAD(5, b_); GLB_STEP(2, c_, false);
;         GLB_LOAD(6, c_); GLB_STEP(3, d_, false);
	v_lshl_add_u64 v[10:11], v[180:181], 0, s[20:21]
	s_add_i32 s20, s16, s13
	v_mfma_f32_16x16x32_bf16 v[150:153], v[64:67], v[56:59], v[60:63]
	global_load_dwordx4 v[76:79], v[8:9], off
	global_load_dwordx4 v[72:75], v[8:9], off offset:1024
	v_lshl_add_u32 v8, s22, 7, v193
	s_ashr_i32 s21, s20, 31
	v_ashrrev_i32_e32 v9, 31, v8
	s_lshl_b64 s[20:21], s[20:21], 17
	v_lshl_add_u64 v[8:9], v[8:9], 2, s[2:3]
	s_or_b32 s20, s20, s19
	v_cvt_pk_bf16_f32 v56, v146, s0
	v_add_u32_e32 v246, v182, v248
	s_mov_b32 m0, s99
	s_nop 0
	global_load_lds_dwordx4 v246, s[24:25]
	global_load_dword v251, v249, s[54:55]
	global_load_dword v251, v249, s[54:55]
	global_load_dword v251, v249, s[54:55]
	global_load_dword v188, v[8:9], off
	global_load_dwordx4 v[20:23], v[10:11], off
	global_load_dwordx4 v[16:19], v[10:11], off offset:1024
	global_load_dwordx4 v[12:15], v[10:11], off offset:2048
	s_nop 0
	global_load_dwordx4 v[8:11], v[10:11], off offset:3072
	s_add_u32 s20, s8, s20
	ds_write_b16 v212, v56
	v_cvt_pk_bf16_f32 v56, v150, s0
	s_addc_u32 s21, s9, s21
	ds_write_b16 v212, v56 offset:4352
	v_cvt_pk_bf16_f32 v56, v147, s0
	s_add_u32 s20, s20, s4
	ds_write_b16 v212, v56 offset:272
	v_cvt_pk_bf16_f32 v56, v151, s0
	s_addc_u32 s21, s21, s5
	ds_write_b16 v212, v56 offset:4624
	v_cvt_pk_bf16_f32 v56, v148, s0
	v_lshl_add_u64 v[68:69], s[20:21], 0, v[176:177]
	ds_write_b16 v212, v56 offset:544
	v_cvt_pk_bf16_f32 v56, v152, s0
	s_add_i32 s20, s11, s17
	ds_write_b16 v212, v56 offset:4896
	v_cvt_pk_bf16_f32 v56, v149, s0
	s_ashr_i32 s21, s20, 31
	ds_write_b16 v212, v56 offset:816
	v_cvt_pk_bf16_f32 v56, v153, s0
	s_lshl_b64 s[22:23], s[20:21], 14
	ds_write_b16 v212, v56 offset:5168
	v_lshl_add_u64 v[56:57], v[178:179], 0, s[22:23]
	s_add_i32 s22, s17, s12
	s_ashr_i32 s23, s22, 31
	s_lshl_b64 s[22:23], s[22:23], 15
	s_add_u32 s22, s54, s22
	global_load_dwordx2 v[194:195], v[68:69], off
	s_waitcnt lgkmcnt(0)
	s_waitcnt vmcnt(29)
	s_barrier
	ds_read_b128 v[140:143], v250 offset:12288
	ds_read_b128 v[132:135], v250 offset:13312
	ds_read_b128 v[128:131], v250 offset:14336
	ds_read_b128 v[124:127], v250 offset:15360
	s_waitcnt lgkmcnt(0)
	s_addc_u32 s23, s55, s23
	s_add_i32 s17, s17, -4
	global_load_dwordx4 v[108:111], v[56:57], off
	global_load_dwordx4 v[96:99], v[56:57], off offset:1024
	v_lshl_add_u32 v56, s20, 7, v193
	s_add_i32 s20, s17, s14
	s_ashr_i32 s21, s20, 31
	s_lshl_b64 s[20:21], s[20:21], 14
	v_lshl_add_u64 v[68:69], v[180:181], 0, s[20:21]
	s_add_i32 s20, s17, s13
	s_ashr_i32 s21, s20, 31
	s_lshl_b64 s[20:21], s[20:21], 17
	s_or_b32 s19, s20, s19
	s_waitcnt vmcnt(26)
	v_pk_mul_f32 v[148:149], v[144:145], v[148:149] op_sel_hi:[0,1]
	v_pk_mul_f32 v[146:147], v[144:145], v[146:147] op_sel_hi:[0,1]
	v_ashrrev_i32_e32 v57, 31, v56
	s_add_u32 s19, s8, s19
	v_mfma_f32_16x16x32_bf16 v[140:143], v[140:143], v[120:123], v[146:149]
	v_lshl_add_u64 v[56:57], v[56:57], 2, s[2:3]
	s_addc_u32 s21, s9, s21
	v_add_u32_e32 v246, v182, v248
	s_mov_b32 m0, s100
	s_nop 0
	global_load_lds_dwordx4 v246, s[22:23]
	global_load_dword v251, v249, s[54:55]
	global_load_dword v251, v249, s[54:55]
	global_load_dword v251, v249, s[54:55]
	global_load_dword v190, v[56:57], off
	global_load_dwordx4 v[64:67], v[68:69], off
	global_load_dwordx4 v[60:63], v[68:69], off offset:1024
	s_nop 0
	global_load_dwordx4 v[56:59], v[68:69], off offset:2048
	s_nop 0
	global_load_dwordx4 v[68:71], v[68:69], off offset:3072
	s_add_u32 s20, s19, s4
	s_addc_u32 s21, s21, s5
	v_mfma_f32_16x16x32_bf16 v[156:159], v[132:135], v[136:139], v[140:143]
	v_mul_f32_e64 v134, v144, v152
	v_mul_f32_e64 v135, v144, v153
	v_pk_mul_f32 v[132:133], v[144:145], v[150:151] op_sel_hi:[0,1]
	v_lshl_add_u64 v[140:141], s[20:21], 0, v[176:177]
	global_load_dwordx2 v[160:161], v[140:141], off
	v_mfma_f32_16x16x32_bf16 v[120:123], v[128:131], v[120:123], v[132:135]
	v_mfma_f32_16x16x32_bf16 v[144:147], v[124:127], v[136:139], v[120:123]
	s_nop 6
	v_cvt_pk_bf16_f32 v120, v156, s0
	ds_write_b16 v212, v120 offset:8704
	v_cvt_pk_bf16_f32 v120, v144, s0
	ds_write_b16 v212, v120 offset:13056
	v_cvt_pk_bf16_f32 v120, v157, s0
	ds_write_b16 v212, v120 offset:8976
	v_cvt_pk_bf16_f32 v120, v145, s0
	ds_write_b16 v212, v120 offset:13328
	v_cvt_pk_bf16_f32 v120, v158, s0
	ds_write_b16 v212, v120 offset:9248
	v_cvt_pk_bf16_f32 v120, v146, s0
	ds_write_b16 v212, v120 offset:13600
	v_cvt_pk_bf16_f32 v120, v159, s0
	ds_write_b16 v212, v120 offset:9520
	v_cvt_pk_bf16_f32 v120, v147, s0
	ds_write_b16 v212, v120 offset:13872
	s_waitcnt lgkmcnt(0)
	s_waitcnt vmcnt(9)
	s_barrier
	ds_read_b128 v[48:51], v250 offset:0
	ds_read_b128 v[36:39], v250 offset:1024
	ds_read_b128 v[52:55], v250 offset:2048
	ds_read_b128 v[40:43], v250 offset:3072
	ds_read_b128 v[88:91], v250 offset:4096
	ds_read_b128 v[80:83], v250 offset:5120
	ds_read_b128 v[92:95], v250 offset:6144
	ds_read_b128 v[84:87], v250 offset:7168
	ds_read_b128 v[116:119], v250 offset:8192
	ds_read_b128 v[100:103], v250 offset:9216
	ds_read_b128 v[112:115], v250 offset:10240
	ds_read_b128 v[104:107], v250 offset:11264
	s_waitcnt lgkmcnt(0)
	v_lshl_add_u64 v[120:121], s[8:9], 0, v[176:177]
	v_lshl_add_u64 v[186:187], v[120:121], 0, s[4:5]
	s_lshl_b32 s8, s18, 12
	s_mov_b32 s9, 32
	s_mov_b32 s18, 4
.LBB0_1281:
	s_add_i32 s19, s18, 3
	s_waitcnt vmcnt(29)
	v_pk_mul_f32 v[130:131], v[158:159], v[192:193] op_sel_hi:[1,0]
	v_pk_mul_f32 v[128:129], v[156:157], v[192:193] op_sel_hi:[1,0]
	v_pk_mul_f32 v[134:135], v[146:147], v[192:193] op_sel_hi:[1,0]
	v_pk_mul_f32 v[132:133], v[144:145], v[192:193] op_sel_hi:[1,0]
	s_and_b64 s[20:21], s[6:7], exec
	v_mfma_f32_16x16x32_bf16 v[48:51], v[48:51], v[44:47], v[128:131]
	s_cselect_b32 s21, s19, s9
	s_add_i32 s22, s21, s11
	s_add_i32 s24, s21, s12
	v_mfma_f32_16x16x32_bf16 v[44:47], v[52:55], v[44:47], v[132:135]
	s_ashr_i32 s23, s22, 31
	ds_read_b128 v[172:175], v210 offset:8704
	ds_read_b128 v[140:143], v210 offset:8768
	ds_read_b128 v[124:127], v210 offset:8832
	ds_read_b128 v[120:123], v210 offset:8896
	s_add_i32 s20, s15, s13
	s_add_i32 s15, s21, -4
	s_ashr_i32 s25, s24, 31
	v_lshl_add_u32 v52, s22, 7, v193
	s_lshl_b64 s[22:23], s[22:23], 14
	s_add_i32 s26, s15, s14
	s_lshl_b64 s[24:25], s[24:25], 15
	v_mfma_f32_16x16x32_bf16 v[36:39], v[36:39], v[28:31], v[48:51]
	s_waitcnt vmcnt(0)
	v_lshlrev_b32_e32 v206, 16, v160
	v_and_b32_e32 v207, 0xffff0000, v160
	v_lshlrev_b32_e32 v208, 16, v161
	v_mfma_f32_16x16x32_bf16 v[28:31], v[40:43], v[28:31], v[44:47]
	v_lshl_add_u64 v[40:41], v[178:179], 0, s[22:23]
	v_and_b32_e32 v209, 0xffff0000, v161
	s_add_i32 s28, s15, s13
	v_ashrrev_i32_e32 v53, 31, v52
	s_ashr_i32 s27, s26, 31
	v_lshl_add_u64 v[42:43], v[184:185], 0, s[24:25]
	global_load_dwordx4 v[160:163], v[40:41], off
	global_load_dwordx4 v[144:147], v[40:41], off offset:1024
	v_lshl_add_u64 v[246:247], v[42:43], 0, v[248:249]
	s_mov_b32 m0, s101
	s_nop 0
	global_load_lds_dwordx4 v[246:247], off
	global_load_dword v251, v249, s[54:55]
	global_load_dword v251, v249, s[54:55]
	global_load_dword v251, v249, s[54:55]
	s_waitcnt lgkmcnt(3)
	v_mfma_f32_16x16x32_bf16 v[32:35], v[172:175], v[32:35], 0
	s_ashr_i32 s21, s20, 31
	s_ashr_i32 s29, s28, 31
	v_lshl_add_u64 v[44:45], v[52:53], 2, s[2:3]
	s_lshl_b64 s[22:23], s[26:27], 14
	s_lshl_b64 s[20:21], s[20:21], 17
	s_lshl_b64 s[24:25], s[28:29], 17
	v_lshl_add_u64 v[40:41], v[180:181], 0, s[22:23]
	global_load_dword v182, v[44:45], off
	global_load_dwordx4 v[152:155], v[40:41], off
	global_load_dwordx4 v[136:139], v[40:41], off offset:1024
	global_load_dwordx4 v[132:135], v[40:41], off offset:2048
	global_load_dwordx4 v[128:131], v[40:41], off offset:3072
	s_add_i32 s19, s18, 4
	s_or_b32 s20, s20, s8
	s_or_b32 s24, s24, s8
	s_cmp_lt_u32 s18, 32
	s_waitcnt lgkmcnt(2)
	v_mfma_f32_16x16x32_bf16 v[24:27], v[140:143], v[24:27], v[32:35]
	s_cselect_b32 s15, s19, 35
	v_cvt_pk_bf16_f32 v40, v36, s0
	v_cvt_pk_bf16_f32 v41, v28, s0
	v_cvt_pk_bf16_f32 v42, v37, s0
	v_cvt_pk_bf16_f32 v43, v29, s0
	v_cvt_pk_bf16_f32 v44, v38, s0
	v_cvt_pk_bf16_f32 v45, v30, s0
	v_cvt_pk_bf16_f32 v48, v39, s0
	v_cvt_pk_bf16_f32 v49, v31, s0
	v_pk_mul_f32 v[38:39], v[188:189], v[38:39] op_sel_hi:[0,1]
	v_pk_mul_f32 v[36:37], v[188:189], v[36:37] op_sel_hi:[0,1]
	v_pk_mul_f32 v[30:31], v[188:189], v[30:31] op_sel_hi:[0,1]
	v_pk_mul_f32 v[28:29], v[188:189], v[28:29] op_sel_hi:[0,1]
	s_sub_i32 s22, 39, s15
	v_lshl_add_u64 v[46:47], v[186:187], 0, s[20:21]
	v_mfma_f32_16x16x32_bf16 v[36:39], v[88:91], v[76:79], v[36:39]
	s_and_b64 s[20:21], s[6:7], exec
	v_lshl_add_u64 v[200:201], v[186:187], 0, s[24:25]
	s_cselect_b32 s15, s15, s22
	v_mfma_f32_16x16x32_bf16 v[28:31], v[92:95], v[76:79], v[28:31]
	global_load_dwordx2 v[204:205], v[200:201], off
	ds_write_b16 v212, v40
	ds_write_b16 v212, v41 offset:4352
	ds_write_b16 v212, v42 offset:272
	ds_write_b16 v212, v43 offset:4624
	ds_write_b16 v212, v44 offset:544
	ds_write_b16 v212, v45 offset:4896
	s_add_i32 s20, s16, s13
	s_waitcnt lgkmcnt(7)
	v_mfma_f32_16x16x32_bf16 v[4:7], v[124:127], v[4:7], v[24:27]
	v_sub_u32_e64 v41, s15, 4 clamp
	s_add_i32 s22, s15, s11
	s_add_i32 s24, s15, s12
	s_ashr_i32 s21, s20, 31
	v_readfirstlane_b32 s15, v41
	v_mfma_f32_16x16x32_bf16 v[32:35], v[80:83], v[72:75], v[36:39]
	s_lshl_b64 s[20:21], s[20:21], 17
	s_add_i32 s26, s15, s13
	s_or_b32 s20, s20, s8
	v_mfma_f32_16x16x32_bf16 v[28:31], v[84:87], v[72:75], v[28:31]
	s_ashr_i32 s27, s26, 31
	s_min_u32 s16, s18, 30
	s_ashr_i32 s23, s22, 31
	s_waitcnt lgkmcnt(6)
	v_mfma_f32_16x16x32_bf16 v[0:3], v[120:123], v[0:3], v[4:7]
	s_ashr_i32 s25, s24, 31
	v_add_u32_e32 v40, s14, v41
	v_lshl_add_u64 v[88:89], v[186:187], 0, s[20:21]
	s_lshl_b64 s[20:21], s[26:27], 17
	s_add_i32 s28, s16, 5
	s_sub_i32 s16, 34, s16
	v_lshl_add_u32 v36, s22, 7, v193
	s_lshl_b64 s[22:23], s[22:23], 14
	s_lshl_b64 s[24:25], s[24:25], 15
	v_ashrrev_i32_e32 v41, 31, v40
	s_or_b32 s20, s20, s8
	v_lshlrev_b32_e32 v198, 16, v196
	v_and_b32_e32 v199, 0xffff0000, v196
	v_lshlrev_b32_e32 v196, 16, v197
	v_and_b32_e32 v197, 0xffff0000, v197
	v_lshlrev_b64 v[38:39], 14, v[40:41]
	v_lshl_add_u64 v[40:41], v[178:179], 0, s[22:23]
	v_cvt_pk_bf16_f32 v93, v28, s0
	v_cvt_pk_bf16_f32 v95, v29, s0
	v_cvt_pk_bf16_f32 v141, v30, s0
	v_cvt_pk_bf16_f32 v143, v31, s0
	v_pk_mul_f32 v[26:27], v[190:191], v[34:35] op_sel_hi:[0,1]
	v_pk_mul_f32 v[24:25], v[190:191], v[32:33] op_sel_hi:[0,1]
	v_pk_mul_f32 v[30:31], v[190:191], v[30:31] op_sel_hi:[0,1]
	v_pk_mul_f32 v[28:29], v[190:191], v[28:29] op_sel_hi:[0,1]
	s_and_b64 s[22:23], s[6:7], exec
	v_mfma_f32_16x16x32_bf16 v[24:27], v[116:119], v[108:111], v[24:27]
	s_cselect_b32 s16, s28, s16
	v_pk_add_f32 v[2:3], v[2:3], v[196:197]
	v_pk_add_f32 v[0:1], v[0:1], v[198:199]
	v_mfma_f32_16x16x32_bf16 v[28:31], v[112:115], v[108:111], v[28:31]
	s_add_i32 s22, s16, s11
	v_cvt_pk_bf16_f32 v0, v0, v1
	v_cvt_pk_bf16_f32 v1, v2, v3
	ds_write_b16 v212, v48 offset:816
	ds_write_b16 v212, v49 offset:5168
	v_ashrrev_i32_e32 v37, 31, v36
	v_lshl_add_u32 v4, s22, 7, v193
	global_store_dwordx2 v[46:47], v[0:1], off
	v_lshl_add_u64 v[42:43], v[184:185], 0, s[24:25]
	v_lshl_add_u64 v[72:73], v[36:37], 2, s[2:3]
	v_lshl_add_u64 v[74:75], v[180:181], 0, v[38:39]
	v_lshl_add_u64 v[76:77], v[186:187], 0, s[20:21]
	v_ashrrev_i32_e32 v5, 31, v4
	s_waitcnt lgkmcnt(0)
	s_barrier
	v_cvt_pk_bf16_f32 v92, v32, s0
	v_cvt_pk_bf16_f32 v94, v33, s0
	v_cvt_pk_bf16_f32 v140, v34, s0
	v_cvt_pk_bf16_f32 v142, v35, s0
	v_mfma_f32_16x16x32_bf16 v[120:123], v[100:103], v[96:99], v[24:27]
	v_lshl_add_u64 v[100:101], v[4:5], 2, s[2:3]
	s_add_i32 s24, s16, s12
	s_add_i32 s16, s16, -4
	v_mfma_f32_16x16x32_bf16 v[124:127], v[104:107], v[96:99], v[28:31]
	global_load_dwordx4 v[44:47], v[40:41], off
	s_nop 1
	global_load_dwordx4 v[28:31], v[40:41], off offset:1024
	v_lshl_add_u64 v[246:247], v[42:43], 0, v[248:249]
	s_mov_b32 m0, s98
	s_nop 0
	global_load_lds_dwordx4 v[246:247], off
	global_load_dword v251, v249, s[54:55]
	global_load_dword v251, v249, s[54:55]
	s_nop 0
	global_load_dword v251, v249, s[54:55]
	s_nop 0
	global_load_dword v192, v[72:73], off
	global_load_dwordx4 v[32:35], v[74:75], off
	global_load_dwordx4 v[24:27], v[74:75], off offset:1024
	global_load_dwordx4 v[4:7], v[74:75], off offset:2048
	global_load_dwordx4 v[0:3], v[74:75], off offset:3072
	global_load_dwordx2 v[196:197], v[76:77], off
	ds_read_b128 v[72:75], v210
	ds_read_b128 v[76:79], v210 offset:64
	ds_read_b128 v[80:83], v210 offset:128
	ds_read_b128 v[84:87], v210 offset:192
	s_add_i32 s20, s17, s13
	s_waitcnt lgkmcnt(3)
	v_mfma_f32_16x16x32_bf16 v[20:23], v[72:75], v[20:23], 0
	s_add_i32 s28, s16, s13
	s_ashr_i32 s21, s20, 31
	s_add_i32 s26, s16, s14
	s_waitcnt lgkmcnt(2)
	v_mfma_f32_16x16x32_bf16 v[16:19], v[76:79], v[16:19], v[20:23]
	s_ashr_i32 s29, s28, 31
	s_min_u32 s17, s18, 29
	s_ashr_i32 s23, s22, 31
	s_waitcnt lgkmcnt(1)
	v_mfma_f32_16x16x32_bf16 v[12:15], v[80:83], v[12:15], v[16:19]
	s_ashr_i32 s25, s24, 31
	s_lshl_b64 s[20:21], s[20:21], 17
	s_ashr_i32 s27, s26, 31
	s_waitcnt lgkmcnt(0)
	v_mfma_f32_16x16x32_bf16 v[8:11], v[84:87], v[8:11], v[12:15]
	s_lshl_b64 s[28:29], s[28:29], 17
	s_add_i32 s30, s17, 6
	s_sub_i32 s17, 33, s17
	s_lshl_b64 s[22:23], s[22:23], 14
	s_lshl_b64 s[24:25], s[24:25], 15
	s_or_b32 s20, s20, s8
	s_lshl_b64 s[26:27], s[26:27], 14
	s_or_b32 s28, s28, s8
	v_lshlrev_b32_e32 v202, 16, v194
	v_and_b32_e32 v203, 0xffff0000, v194
	v_lshlrev_b32_e32 v194, 16, v195
	v_and_b32_e32 v195, 0xffff0000, v195
	v_lshl_add_u64 v[108:109], v[186:187], 0, s[20:21]
	s_and_b64 s[20:21], s[6:7], exec
	s_cselect_b32 s17, s30, s17
	v_pk_add_f32 v[10:11], v[10:11], v[194:195]
	v_pk_add_f32 v[8:9], v[8:9], v[202:203]
	s_add_i32 s20, s17, s11
	v_cvt_pk_bf16_f32 v8, v8, v9
	v_cvt_pk_bf16_f32 v9, v10, v11
	ds_write_b16 v212, v92 offset:8704
	ds_write_b16 v212, v93 offset:13056
	ds_write_b16 v212, v94 offset:8976
	ds_write_b16 v212, v95 offset:13328
	ds_write_b16 v212, v140 offset:9248
	ds_write_b16 v212, v141 offset:13600
	ds_write_b16 v212, v142 offset:9520
	ds_write_b16 v212, v143 offset:13872
	v_lshl_add_u32 v92, s20, 7, v193
	global_store_dwordx2 v[88:89], v[8:9], off
	v_lshl_add_u64 v[90:91], v[178:179], 0, s[22:23]
	v_lshl_add_u64 v[96:97], v[184:185], 0, s[24:25]
	v_ashrrev_i32_e32 v93, 31, v92
	s_waitcnt lgkmcnt(0)
	s_barrier
	v_lshl_add_u64 v[142:143], v[92:93], 2, s[2:3]
	global_load_dwordx4 v[76:79], v[90:91], off
	global_load_dwordx4 v[72:75], v[90:91], off offset:1024
	s_nop 0
	v_lshl_add_u64 v[246:247], v[96:97], 0, v[248:249]
	s_mov_b32 m0, s99
	s_nop 0
	global_load_lds_dwordx4 v[246:247], off
	global_load_dword v251, v249, s[54:55]
	global_load_dword v251, v249, s[54:55]
	global_load_dword v251, v249, s[54:55]
	ds_read_b128 v[96:99], v210 offset:8704
	v_lshl_add_u64 v[104:105], v[180:181], 0, s[26:27]
	global_load_dword v188, v[100:101], off
	global_load_dwordx4 v[20:23], v[104:105], off
	ds_read_b128 v[100:103], v210 offset:8768
	v_lshl_add_u64 v[106:107], v[186:187], 0, s[28:29]
	global_load_dwordx4 v[16:19], v[104:105], off offset:1024
	global_load_dwordx4 v[12:15], v[104:105], off offset:2048
	global_load_dwordx4 v[8:11], v[104:105], off offset:3072
	global_load_dwordx2 v[194:195], v[106:107], off
	ds_read_b128 v[104:107], v210 offset:8832
	s_waitcnt lgkmcnt(2)
	v_mfma_f32_16x16x32_bf16 v[64:67], v[96:99], v[64:67], 0
	ds_read_b128 v[96:99], v210 offset:8896
	s_add_i32 s22, s17, s12
	s_add_i32 s17, s17, -4
	s_waitcnt lgkmcnt(2)
	v_mfma_f32_16x16x32_bf16 v[60:63], v[100:103], v[60:63], v[64:67]
	v_cvt_pk_bf16_f32 v110, v120, s0
	v_cvt_pk_bf16_f32 v114, v121, s0
	v_cvt_pk_bf16_f32 v117, v126, s0
	s_waitcnt lgkmcnt(1)
	v_mfma_f32_16x16x32_bf16 v[56:59], v[104:107], v[56:59], v[60:63]
	s_ashr_i32 s21, s20, 31
	s_add_i32 s24, s17, s14
	v_cvt_pk_bf16_f32 v111, v124, s0
	s_waitcnt lgkmcnt(0)
	v_mfma_f32_16x16x32_bf16 v[56:59], v[96:99], v[68:71], v[56:59]
	v_cvt_pk_bf16_f32 v115, v125, s0
	v_cvt_pk_bf16_f32 v116, v122, s0
	v_cvt_pk_bf16_f32 v118, v123, s0
	v_cvt_pk_bf16_f32 v119, v127, s0
	s_ashr_i32 s23, s22, 31
	s_nop 2
	v_pk_add_f32 v[58:59], v[58:59], v[208:209]
	v_pk_add_f32 v[56:57], v[56:57], v[206:207]
	s_lshl_b64 s[20:21], s[20:21], 14
	v_cvt_pk_bf16_f32 v56, v56, v57
	v_cvt_pk_bf16_f32 v57, v58, v59
	s_ashr_i32 s25, s24, 31
	ds_write_b16 v212, v110
	ds_write_b16 v212, v111 offset:4352
	ds_write_b16 v212, v114 offset:272
	ds_write_b16 v212, v115 offset:4624
	ds_write_b16 v212, v116 offset:544
	ds_write_b16 v212, v117 offset:4896
	ds_write_b16 v212, v118 offset:816
	ds_write_b16 v212, v119 offset:5168
	global_store_dwordx2 v[108:109], v[56:57], off
	s_lshl_b64 s[22:23], s[22:23], 15
	s_lshl_b64 s[24:25], s[24:25], 14
	v_lshl_add_u64 v[112:113], v[178:179], 0, s[20:21]
	s_waitcnt lgkmcnt(0)
	s_waitcnt vmcnt(36)
	s_barrier
; __device__ __forceinline__ void gla_scan(LAS unsigned char* lds, int bx, int G, const bf16_t* KS, const bf16_t* QD, const bf16_t* VT, const float* DEC, bf16_t* Of, bf16_t* Ob) {
;     ...
;         for (int step = 4; step < GLA_NCH; step += 4) {
;             GLB_LOAD(step + 3, d_); GLB_STEP(step, a_, true);
;             GLB_LOAD(step + 4, a_); GLB_STEP(step + 1, b_, true);
;             GLB_LOAD(step + 5, b_); GLB_STEP(step + 2, c_, true);
;             GLB_LOAD(step + 6, c_); GLB_STEP(step + 3, d_, true);
;         }
	ds_read_b128 v[168:171], v250 offset:12288
	ds_read_b128 v[156:159], v250 offset:13312
	ds_read_b128 v[164:167], v250 offset:14336
	ds_read_b128 v[148:151], v250 offset:15360
	s_waitcnt lgkmcnt(0)
	v_lshl_add_u64 v[140:141], v[184:185], 0, s[22:23]
	v_lshl_add_u64 v[172:173], v[180:181], 0, s[24:25]
	global_load_dwordx4 v[108:111], v[112:113], off
	global_load_dwordx4 v[96:99], v[112:113], off offset:1024
	v_lshl_add_u64 v[246:247], v[140:141], 0, v[248:249]
	s_mov_b32 m0, s100
	s_nop 0
	global_load_lds_dwordx4 v[246:247], off
	global_load_dword v251, v249, s[54:55]
	s_nop 0
	global_load_dword v251, v249, s[54:55]
	global_load_dword v251, v249, s[54:55]
	global_load_dword v190, v[142:143], off
	global_load_dwordx4 v[64:67], v[172:173], off
	global_load_dwordx4 v[60:63], v[172:173], off offset:1024
	global_load_dwordx4 v[56:59], v[172:173], off offset:2048
	s_add_i32 s26, s17, s13
	s_ashr_i32 s27, s26, 31
	s_lshl_b64 s[26:27], s[26:27], 17
	s_or_b32 s26, s26, s8
	v_lshl_add_u64 v[174:175], v[186:187], 0, s[26:27]
	s_waitcnt vmcnt(42)
	v_pk_mul_f32 v[70:71], v[182:183], v[122:123] op_sel_hi:[0,1]
	v_pk_mul_f32 v[68:69], v[182:183], v[120:121] op_sel_hi:[0,1]
	v_pk_mul_f32 v[126:127], v[182:183], v[126:127] op_sel_hi:[0,1]
	v_pk_mul_f32 v[124:125], v[182:183], v[124:125] op_sel_hi:[0,1]
	v_mfma_f32_16x16x32_bf16 v[120:123], v[168:171], v[160:163], v[68:71]
	s_waitcnt vmcnt(37)
	v_lshlrev_b32_e32 v170, 16, v204
	v_and_b32_e32 v171, 0xffff0000, v204
	s_add_i32 s9, s9, -4
	global_load_dwordx4 v[68:71], v[172:173], off offset:3072
	v_mfma_f32_16x16x32_bf16 v[124:127], v[164:167], v[160:163], v[124:127]
	global_load_dwordx2 v[160:161], v[174:175], off
	ds_read_b128 v[140:143], v210
	ds_read_b128 v[162:165], v210 offset:64
	s_cmp_gt_u32 s18, 31
	v_mfma_f32_16x16x32_bf16 v[156:159], v[156:159], v[144:147], v[120:123]
	s_nop 2
	ds_read_b128 v[120:123], v210 offset:128
	ds_read_b128 v[166:169], v210 offset:192
	s_mov_b32 s18, s19
	v_mfma_f32_16x16x32_bf16 v[144:147], v[148:151], v[144:147], v[124:127]
	v_lshlrev_b32_e32 v148, 16, v205
	v_and_b32_e32 v149, 0xffff0000, v205
	v_cvt_pk_bf16_f32 v150, v158, s0
	s_waitcnt lgkmcnt(3)
	v_mfma_f32_16x16x32_bf16 v[124:127], v[140:143], v[152:155], 0
	v_cvt_pk_bf16_f32 v140, v156, s0
	s_nop 1
	v_cvt_pk_bf16_f32 v151, v146, s0
	v_cvt_pk_bf16_f32 v141, v144, s0
	s_waitcnt lgkmcnt(2)
	v_mfma_f32_16x16x32_bf16 v[124:127], v[162:165], v[136:139], v[124:127]
	v_cvt_pk_bf16_f32 v142, v157, s0
	v_cvt_pk_bf16_f32 v143, v145, s0
	v_cvt_pk_bf16_f32 v152, v159, s0
	s_waitcnt lgkmcnt(1)
	v_mfma_f32_16x16x32_bf16 v[120:123], v[120:123], v[132:135], v[124:127]
	v_cvt_pk_bf16_f32 v153, v147, s0
	ds_write_b16 v212, v140 offset:8704
	ds_write_b16 v212, v141 offset:13056
	ds_write_b16 v212, v142 offset:8976
	ds_write_b16 v212, v143 offset:13328
	ds_write_b16 v212, v150 offset:9248
	ds_write_b16 v212, v151 offset:13600
	ds_write_b16 v212, v152 offset:9520
	ds_write_b16 v212, v153 offset:13872
	s_waitcnt lgkmcnt(8)
	v_mfma_f32_16x16x32_bf16 v[120:123], v[166:169], v[128:131], v[120:123]
	s_nop 7
	v_pk_add_f32 v[122:123], v[122:123], v[148:149]
	v_pk_add_f32 v[120:121], v[120:121], v[170:171]
	s_nop 0
	v_cvt_pk_bf16_f32 v120, v120, v121
	v_cvt_pk_bf16_f32 v121, v122, v123
	global_store_dwordx2 v[200:201], v[120:121], off
	s_waitcnt lgkmcnt(0)
	s_waitcnt vmcnt(10)
	s_barrier
	ds_read_b128 v[48:51], v250 offset:0
	ds_read_b128 v[36:39], v250 offset:1024
	ds_read_b128 v[52:55], v250 offset:2048
	ds_read_b128 v[40:43], v250 offset:3072
	ds_read_b128 v[88:91], v250 offset:4096
	ds_read_b128 v[80:83], v250 offset:5120
	ds_read_b128 v[92:95], v250 offset:6144
	ds_read_b128 v[84:87], v250 offset:7168
	ds_read_b128 v[116:119], v250 offset:8192
	ds_read_b128 v[100:103], v250 offset:9216
	ds_read_b128 v[112:115], v250 offset:10240
	ds_read_b128 v[104:107], v250 offset:11264
	s_waitcnt lgkmcnt(0)
	s_cbranch_scc0 .LBB0_1281
	s_add_i32 s10, s10, s34
	s_cmpk_gt_i32 s10, 0xff
	s_cbranch_scc0 .LBB0_1280
